# attention softmax: (s-mx)*log2e computed as one fma with precomputed -mx*log2e
# baseline (speedup 1.0000x reference)
; __device__ __forceinline__ void attn_item(const Ctx& C, int it, int itn, u32x4 (&kv)[4], u32x4 (&vv)[4], u32x4 (&qv)[2]) {
;     ...
;     const int fr = lane & 15, quad = lane >> 4;
;     bf16x8 qf[2];
;     qf[0] = *(const bf16x8*)(Qs + (16 * w + fr) * 72 + 8 * quad); qf[1] = *(const bf16x8*)(Qs + (16 * w + fr) * 72 + 32 + 8 * quad);
;     f32x4 sc[9];
; #pragma unroll
;     for (int kt = 0; kt < 9; ++kt) { const bf16_t* kr = Ks + (16 * (w + kt) + fr) * 72 + 8 * quad;
;         const bf16x8 k0 = *(const bf16x8*)kr, k1 = *(const bf16x8*)(kr + 32);
;         f32x4 z4 = {0.f, 0.f, 0.f, 0.f};
;         z4 = __builtin_amdgcn_mfma_f32_16x16x32_bf16(k0, qf[0], z4, 0, 0, 0);
;         sc[kt] = __builtin_amdgcn_mfma_f32_16x16x32_bf16(k1, qf[1], z4, 0, 0, 0); }
;     const int a = 16 * w + fr;
;     float mx = -1e30f;
; #pragma unroll
;     for (int kt = 0; kt < 9; ++kt)
; #pragma unroll
;         for (int rg = 0; rg < 4; ++rg) { const int cidx = 16 * (w + kt) + 4 * quad + rg, rel = cidx - 64 - a, ik = 128 * jb - 64 + cidx;
;             const bool valid = (rel >= -64) && (rel <= 64) && (ik >= 0) && (ik < n);
;             const int bi = rel < -64 ? 0 : (rel > 64 ? 128 : rel + 64);
;             const float s = valid ? sc[kt][rg] * 0.125f + bt[bi] : -1e30f;
;             sc[kt][rg] = s; mx = fmaxf(mx, s); }
.LBB0_359:
	s_waitcnt lgkmcnt(0)
	s_barrier
	ds_read_b32 v212, v98
	ds_read_b32 v213, v100
	ds_read_b32 v214, v102
	ds_read_b32 v215, v104
	ds_read_b32 v223, v106
	ds_read_b32 v228, v108
	ds_read_b32 v229, v110
	ds_read_b32 v230, v112
	ds_read_b32 v231, v114
	ds_read_b32 v232, v116
	ds_read_b32 v233, v118
	ds_read_b32 v234, v120
	ds_read_b32 v235, v122
	ds_read_b32 v236, v124
	ds_read_b32 v237, v126
	ds_read_b32 v238, v128
	ds_read_b32 v240, v130
	ds_read_b32 v241, v132
	ds_read_b32 v242, v134
	ds_read_b32 v243, v136
	ds_read_b32 v244, v138
	ds_read_b32 v245, v140
	ds_read_b32 v246, v142
	ds_read_b32 v247, v144
	ds_read_b32 v248, v146
	ds_read_b32 v249, v148
	ds_read_b32 v250, v150
	ds_read_b128 v[40:43], v85 offset:36864
	ds_read_b128 v[194:197], v85 offset:36928
	ds_read_b128 v[44:47], v87
	ds_read_b128 v[48:51], v87 offset:64
	s_waitcnt lgkmcnt(1)
	v_mfma_f32_16x16x32_bf16 v[44:47], v[44:47], v[40:43], 0
	s_lshr_b32 s0, 32, s52
	s_and_b32 s47, s36, 31
	s_add_i32 s0, s0, -1
	s_waitcnt lgkmcnt(0)
	v_mfma_f32_16x16x32_bf16 v[74:77], v[48:51], v[194:197], v[44:47]
	s_nop 2
	ds_read_b128 v[44:47], v173
	ds_read_b128 v[48:51], v173 offset:64
	s_and_b32 s0, s0, s47
	s_lshl_b32 s46, s0, 7
	s_waitcnt lgkmcnt(1)
	v_mfma_f32_16x16x32_bf16 v[44:47], v[44:47], v[40:43], 0
	s_sub_i32 s48, s46, 64
	v_add_u32_e32 v64, s48, v89
	v_readlane_b32 s0, v255, 7
	s_waitcnt lgkmcnt(0)
	v_mfma_f32_16x16x32_bf16 v[70:73], v[48:51], v[194:197], v[44:47]
	s_nop 2
	ds_read_b128 v[44:47], v174
	ds_read_b128 v[48:51], v174 offset:64
	s_lshr_b32 s53, 0x1000, s52
	v_cmp_lt_i32_e32 vcc, -1, v64
	s_waitcnt lgkmcnt(1)
	v_mfma_f32_16x16x32_bf16 v[44:47], v[44:47], v[40:43], 0
	v_readlane_b32 s1, v255, 8
	s_and_b64 s[0:1], s[0:1], vcc
	v_cmp_gt_i32_e32 vcc, s53, v64
	s_waitcnt lgkmcnt(0)
	v_mfma_f32_16x16x32_bf16 v[66:69], v[48:51], v[194:197], v[44:47]
	s_nop 2
	ds_read_b128 v[44:47], v175
	ds_read_b128 v[48:51], v175 offset:64
	s_and_b64 s[68:69], s[0:1], vcc
	s_waitcnt lgkmcnt(1)
	v_mfma_f32_16x16x32_bf16 v[44:47], v[44:47], v[40:43], 0
	s_waitcnt lgkmcnt(0)
	v_mfma_f32_16x16x32_bf16 v[60:63], v[48:51], v[194:197], v[44:47]
	s_nop 5
	ds_read_b128 v[44:47], v176
	ds_read_b128 v[48:51], v176 offset:64
	s_waitcnt lgkmcnt(1)
	v_mfma_f32_16x16x32_bf16 v[44:47], v[44:47], v[40:43], 0
	s_waitcnt lgkmcnt(0)
	v_mfma_f32_16x16x32_bf16 v[56:59], v[48:51], v[194:197], v[44:47]
	s_nop 5
	ds_read_b128 v[44:47], v177
	ds_read_b128 v[48:51], v177 offset:64
	s_waitcnt lgkmcnt(1)
	v_mfma_f32_16x16x32_bf16 v[44:47], v[44:47], v[40:43], 0
	s_waitcnt lgkmcnt(0)
	v_mfma_f32_16x16x32_bf16 v[52:55], v[48:51], v[194:197], v[44:47]
	s_nop 5
	ds_read_b128 v[44:47], v183
	ds_read_b128 v[48:51], v183 offset:64
	s_waitcnt lgkmcnt(1)
	v_mfma_f32_16x16x32_bf16 v[44:47], v[44:47], v[40:43], 0
	s_waitcnt lgkmcnt(0)
	v_mfma_f32_16x16x32_bf16 v[48:51], v[48:51], v[194:197], v[44:47]
	s_nop 5
	ds_read_b128 v[44:47], v192
	ds_read_b128 v[198:201], v192 offset:64
	s_waitcnt lgkmcnt(1)
	v_mfma_f32_16x16x32_bf16 v[44:47], v[44:47], v[40:43], 0
	s_waitcnt lgkmcnt(0)
	v_mfma_f32_16x16x32_bf16 v[44:47], v[198:201], v[194:197], v[44:47]
	ds_read_b128 v[198:201], v193
	ds_read_b128 v[202:205], v193 offset:64
	s_waitcnt lgkmcnt(1)
	v_mfma_f32_16x16x32_bf16 v[40:43], v[198:201], v[40:43], 0
	s_waitcnt lgkmcnt(0)
	v_mfma_f32_16x16x32_bf16 v[40:43], v[202:205], v[194:197], v[40:43]
	v_lshrrev_b32_e32 v178, 6, v224
	v_lshlrev_b32_e32 v178, 4, v178
	v_and_b32_e32 v179, 15, v224
	v_add_u32_e32 v179, v178, v179
	s_sub_i32 s0, 0, s48
	v_max_i32_e32 v180, s0, v179
	s_sub_i32 s1, s53, s48
	s_add_i32 s1, s1, -1
	v_add_u32_e32 v179, 0x80, v179
	v_min_i32_e32 v181, s1, v179
	v_bfe_u32 v179, v224, 4, 2
	v_lshl_add_u32 v178, v179, 2, v178
	v_sub_u32_e32 v188, v178, v180
	v_sub_u32_e32 v189, v181, v180
	v_mov_b32_e32 v179, 0xf149f2ca
	v_add_u32_e32 v190, 0, v188
	v_cmp_ge_u32_e32 vcc, v189, v190
	v_fmac_f32_e32 v212, 0x3e000000, v74
	v_add_u32_e32 v191, 1, v188
	v_cndmask_b32_e32 v195, v179, v212, vcc
	ds_read_b32 v212, v152
	v_cmp_ge_u32_e32 vcc, v189, v191
	v_fmac_f32_e32 v213, 0x3e000000, v75
	v_add_u32_e32 v190, 2, v188
	v_cndmask_b32_e32 v91, v179, v213, vcc
	ds_read_b32 v213, v154
	v_cmp_ge_u32_e32 vcc, v189, v190
	v_fmac_f32_e32 v214, 0x3e000000, v76
	v_add_u32_e32 v191, 3, v188
	v_cndmask_b32_e32 v194, v179, v214, vcc
	ds_read_b32 v214, v156
	v_cmp_ge_u32_e32 vcc, v189, v191
	v_fmac_f32_e32 v215, 0x3e000000, v77
	v_add_u32_e32 v190, 16, v188
	v_cndmask_b32_e32 v79, v179, v215, vcc
	ds_read_b32 v215, v158
	v_cmp_ge_u32_e32 vcc, v189, v190
	v_fmac_f32_e32 v223, 0x3e000000, v70
	v_add_u32_e32 v191, 17, v188
	v_cndmask_b32_e32 v74, v179, v223, vcc
	ds_read_b32 v223, v160
	v_cmp_ge_u32_e32 vcc, v189, v191
	v_fmac_f32_e32 v228, 0x3e000000, v71
	v_add_u32_e32 v190, 18, v188
	v_cndmask_b32_e32 v64, v179, v228, vcc
	ds_read_b32 v228, v162
	v_cmp_ge_u32_e32 vcc, v189, v190
	v_fmac_f32_e32 v229, 0x3e000000, v72
	v_add_u32_e32 v191, 19, v188
	v_cndmask_b32_e32 v75, v179, v229, vcc
	ds_read_b32 v229, v164
	v_cmp_ge_u32_e32 vcc, v189, v191
	v_fmac_f32_e32 v230, 0x3e000000, v73
	v_add_u32_e32 v190, 32, v188
	v_cndmask_b32_e32 v70, v179, v230, vcc
	ds_read_b32 v230, v166
	v_cmp_ge_u32_e32 vcc, v189, v190
	v_fmac_f32_e32 v231, 0x3e000000, v66
	v_add_u32_e32 v191, 33, v188
	v_cndmask_b32_e32 v72, v179, v231, vcc
	ds_read_b32 v231, v168
	v_cmp_ge_u32_e32 vcc, v189, v191
	v_fmac_f32_e32 v232, 0x3e000000, v67
	v_add_u32_e32 v190, 34, v188
	v_cndmask_b32_e32 v71, v179, v232, vcc
	v_cmp_ge_u32_e32 vcc, v189, v190
	v_fmac_f32_e32 v233, 0x3e000000, v68
	v_add_u32_e32 v191, 35, v188
	v_cndmask_b32_e32 v73, v179, v233, vcc
	v_cmp_ge_u32_e32 vcc, v189, v191
; __device__ __forceinline__ unsigned cvt_pk_bf16(float lo, float hi) { f32x2_t v = {lo, hi}; bf2_t r = __builtin_convertvector(v, bf2_t); return __builtin_bit_cast(unsigned, r); }
; __device__ __forceinline__ void attn_item(const Ctx& C, int it, int itn, u32x4 (&kv)[4], u32x4 (&vv)[4], u32x4 (&qv)[2]) {
;     ...
;     const int a = 16 * w + fr;
;     float mx = -1e30f;
; #pragma unroll
;     for (int kt = 0; kt < 9; ++kt)
; #pragma unroll
;         for (int rg = 0; rg < 4; ++rg) { const int cidx = 16 * (w + kt) + 4 * quad + rg, rel = cidx - 64 - a, ik = 128 * jb - 64 + cidx;
;             const bool valid = (rel >= -64) && (rel <= 64) && (ik >= 0) && (ik < n);
;             const int bi = rel < -64 ? 0 : (rel > 64 ? 128 : rel + 64);
;             const float s = valid ? sc[kt][rg] * 0.125f + bt[bi] : -1e30f;
;             sc[kt][rg] = s; mx = fmaxf(mx, s); }
;     mx = fmaxf(mx, __shfl_xor(mx, 16)); mx = fmaxf(mx, __shfl_xor(mx, 32));
;     float lsum = 0.f;
; #pragma unroll
;     for (int kt = 0; kt < 9; ++kt)
; #pragma unroll
;         for (int rg = 0; rg < 4; ++rg) { const float s = sc[kt][rg]; const float p = (s > -1e29f) ? __expf(s - mx) : 0.f; sc[kt][rg] = p; lsum += p; }
;     lsum += __shfl_xor(lsum, 16); lsum += __shfl_xor(lsum, 32);
;     f32x4 oo[4];
; #pragma unroll
;     for (int dt = 0; dt < 4; ++dt) oo[dt] = (f32x4){0.f, 0.f, 0.f, 0.f};
; #pragma unroll
;     for (int pp = 0; pp < 5; ++pp) { const int ktA = 2 * pp, ktB = 2 * pp + 1, ktBc = ktB < 9 ? ktB : 8;
;         union { bf16x8 v; unsigned u[4]; } pf;
;         pf.u[0] = cvt_pk_bf16(sc[ktA][0], sc[ktA][1]); pf.u[1] = cvt_pk_bf16(sc[ktA][2], sc[ktA][3]);
;         if (ktB < 9) { pf.u[2] = cvt_pk_bf16(sc[ktBc][0], sc[ktBc][1]); pf.u[3] = cvt_pk_bf16(sc[ktBc][2], sc[ktBc][3]); } else { pf.u[2] = 0u; pf.u[3] = 0u; }
	v_fmac_f32_e32 v234, 0x3e000000, v69
	v_add_u32_e32 v190, 48, v188
	v_cndmask_b32_e32 v66, v179, v234, vcc
	v_cmp_ge_u32_e32 vcc, v189, v190
	v_fmac_f32_e32 v235, 0x3e000000, v60
	v_add_u32_e32 v191, 49, v188
	v_cndmask_b32_e32 v69, v179, v235, vcc
	v_cmp_ge_u32_e32 vcc, v189, v191
	v_fmac_f32_e32 v236, 0x3e000000, v61
	v_add_u32_e32 v190, 50, v188
	v_cndmask_b32_e32 v67, v179, v236, vcc
	v_cmp_ge_u32_e32 vcc, v189, v190
	v_fmac_f32_e32 v237, 0x3e000000, v62
	v_add_u32_e32 v191, 51, v188
	v_cndmask_b32_e32 v68, v179, v237, vcc
	v_cmp_ge_u32_e32 vcc, v189, v191
	v_fmac_f32_e32 v238, 0x3e000000, v63
	v_add_u32_e32 v190, 64, v188
	v_cndmask_b32_e32 v60, v179, v238, vcc
	v_cmp_ge_u32_e32 vcc, v189, v190
	v_fmac_f32_e32 v240, 0x3e000000, v56
	v_add_u32_e32 v191, 0x41, v188
	v_cndmask_b32_e32 v62, v179, v240, vcc
	v_cmp_ge_u32_e32 vcc, v189, v191
	v_fmac_f32_e32 v241, 0x3e000000, v57
	v_add_u32_e32 v190, 0x42, v188
	v_cndmask_b32_e32 v61, v179, v241, vcc
	v_cmp_ge_u32_e32 vcc, v189, v190
	v_fmac_f32_e32 v242, 0x3e000000, v58
	v_add_u32_e32 v191, 0x43, v188
	v_cndmask_b32_e32 v63, v179, v242, vcc
	v_cmp_ge_u32_e32 vcc, v189, v191
	v_fmac_f32_e32 v243, 0x3e000000, v59
	v_add_u32_e32 v190, 0x50, v188
	v_cndmask_b32_e32 v57, v179, v243, vcc
	v_cmp_ge_u32_e32 vcc, v189, v190
	v_fmac_f32_e32 v244, 0x3e000000, v52
	v_add_u32_e32 v191, 0x51, v188
	v_cndmask_b32_e32 v59, v179, v244, vcc
	v_cmp_ge_u32_e32 vcc, v189, v191
	v_fmac_f32_e32 v245, 0x3e000000, v53
	v_add_u32_e32 v190, 0x52, v188
	v_cndmask_b32_e32 v56, v179, v245, vcc
	v_cmp_ge_u32_e32 vcc, v189, v190
	v_fmac_f32_e32 v246, 0x3e000000, v54
	v_add_u32_e32 v191, 0x53, v188
	v_cndmask_b32_e32 v58, v179, v246, vcc
	v_cmp_ge_u32_e32 vcc, v189, v191
	v_fmac_f32_e32 v247, 0x3e000000, v55
	v_add_u32_e32 v190, 0x60, v188
	v_cndmask_b32_e32 v53, v179, v247, vcc
	v_cmp_ge_u32_e32 vcc, v189, v190
	v_fmac_f32_e32 v248, 0x3e000000, v48
	v_add_u32_e32 v191, 0x61, v188
	v_cndmask_b32_e32 v55, v179, v248, vcc
	v_cmp_ge_u32_e32 vcc, v189, v191
	v_fmac_f32_e32 v249, 0x3e000000, v49
	v_add_u32_e32 v190, 0x62, v188
	v_cndmask_b32_e32 v52, v179, v249, vcc
	v_cmp_ge_u32_e32 vcc, v189, v190
	v_fmac_f32_e32 v250, 0x3e000000, v50
	v_add_u32_e32 v191, 0x63, v188
	v_cndmask_b32_e32 v54, v179, v250, vcc
	s_waitcnt lgkmcnt(0)
	v_cmp_ge_u32_e32 vcc, v189, v191
	v_fmac_f32_e32 v212, 0x3e000000, v51
	v_add_u32_e32 v190, 0x70, v188
	v_cndmask_b32_e32 v49, v179, v212, vcc
	v_cmp_ge_u32_e32 vcc, v189, v190
	v_fmac_f32_e32 v213, 0x3e000000, v44
	v_add_u32_e32 v191, 0x71, v188
	v_cndmask_b32_e32 v50, v179, v213, vcc
	v_cmp_ge_u32_e32 vcc, v189, v191
	v_fmac_f32_e32 v214, 0x3e000000, v45
	v_add_u32_e32 v190, 0x72, v188
	v_cndmask_b32_e32 v48, v179, v214, vcc
	v_cmp_ge_u32_e32 vcc, v189, v190
	v_fmac_f32_e32 v215, 0x3e000000, v46
	v_add_u32_e32 v191, 0x73, v188
	v_cndmask_b32_e32 v45, v179, v215, vcc
	v_cmp_ge_u32_e32 vcc, v189, v191
	v_fmac_f32_e32 v223, 0x3e000000, v47
	v_add_u32_e32 v190, 0x80, v188
	v_cndmask_b32_e32 v44, v179, v223, vcc
	v_cmp_ge_u32_e32 vcc, v189, v190
	v_fmac_f32_e32 v228, 0x3e000000, v40
	v_add_u32_e32 v191, 0x81, v188
	v_cndmask_b32_e32 v47, v179, v228, vcc
	v_cmp_ge_u32_e32 vcc, v189, v191
	v_fmac_f32_e32 v229, 0x3e000000, v41
	v_add_u32_e32 v190, 0x82, v188
	v_cndmask_b32_e32 v46, v179, v229, vcc
	v_cmp_ge_u32_e32 vcc, v189, v190
	v_fmac_f32_e32 v230, 0x3e000000, v42
	v_add_u32_e32 v191, 0x83, v188
	v_cndmask_b32_e32 v51, v179, v230, vcc
	v_cmp_ge_u32_e32 vcc, v189, v191
	v_fmac_f32_e32 v231, 0x3e000000, v43
	s_nop 0
	v_cndmask_b32_e32 v41, v179, v231, vcc
	s_mov_b32 s0, 0xf149f2ca
	v_max3_f32 v40, v195, s0, v91
	v_max3_f32 v40, v40, v194, v79
	v_max3_f32 v40, v40, v74, v64
	v_max3_f32 v40, v40, v75, v70
	v_max3_f32 v40, v40, v72, v71
	v_max3_f32 v40, v40, v73, v66
	v_max3_f32 v40, v40, v69, v67
	v_max3_f32 v40, v40, v68, v60
	v_max3_f32 v40, v40, v62, v61
	v_max3_f32 v40, v40, v63, v57
	v_max3_f32 v40, v40, v59, v56
	v_max3_f32 v40, v40, v58, v53
	v_max3_f32 v40, v40, v55, v52
	v_max3_f32 v40, v40, v54, v49
	v_max3_f32 v40, v40, v50, v48
	v_max3_f32 v40, v40, v45, v44
	v_max3_f32 v40, v40, v47, v46
	v_max3_f32 v40, v40, v51, v41
	ds_bpermute_b32 v42, v169, v40
	s_mov_b32 s1, 0x3fb8aa3b
	s_sub_i32 s0, 5, s52
	s_lshr_b32 s0, s47, s0
	s_waitcnt lgkmcnt(0)
	v_max_f32_e32 v42, v42, v42
	v_max_f32_e32 v40, v40, v42
	ds_bpermute_b32 v42, v170, v40
	s_waitcnt lgkmcnt(0)
	v_max_f32_e32 v42, v42, v42
	v_max_f32_e32 v42, v40, v42
	v_mul_f32_e32 v178, 0xbfb8aa3b, v42
	v_fma_f32 v40, v195, s1, v178
	v_fma_f32 v43, v91, s1, v178
	v_exp_f32_e32 v40, v40
	v_exp_f32_e32 v43, v43
	v_add_f32_e32 v76, 0, v40
	s_nop 0
	v_add_f32_e32 v77, v43, v76
	v_fma_f32 v76, v194, s1, v178
	v_exp_f32_e32 v76, v76
	v_cvt_pk_bf16_f32 v196, v40, v43
	s_nop 0
	v_add_f32_e32 v91, v76, v77
	v_fma_f32 v77, v79, s1, v178
	v_exp_f32_e32 v77, v77
	s_nop 1
	v_fma_f32 v74, v74, s1, v178
	v_exp_f32_e32 v74, v74
	v_add_f32_e32 v79, v77, v91
	v_cvt_pk_bf16_f32 v197, v76, v77
	v_fma_f32 v64, v64, s1, v178
	v_exp_f32_e32 v64, v64
	v_add_f32_e32 v91, v74, v79
	v_mov_b32_e32 v79, v64
	v_fma_f32 v75, v75, s1, v178
	v_exp_f32_e32 v75, v75
	v_add_f32_e32 v64, v79, v91
	v_cvt_pk_bf16_f32 v198, v74, v79
	v_fma_f32 v70, v70, s1, v178
	v_exp_f32_e32 v70, v70
	v_add_f32_e32 v64, v75, v64
	v_mov_b32_e32 v91, v70
	v_add_f32_e32 v70, v91, v64
	v_fma_f32 v64, v72, s1, v178
	v_exp_f32_e32 v64, v64
	v_cvt_pk_bf16_f32 v199, v75, v91
	ds_read_b64_tr_b16 v[76:77], v171 offset:57600
	ds_read_b64_tr_b16 v[74:75], v171 offset:55296
	ds_read_b64_tr_b16 v[200:201], v171 offset:55328
	v_add_f32_e32 v72, v64, v70
	v_fma_f32 v70, v71, s1, v178
	v_fma_f32 v71, v73, s1, v178
	v_exp_f32_e32 v70, v70
	v_exp_f32_e32 v71, v71
	ds_read_b64_tr_b16 v[202:203], v171 offset:57632
	v_add_f32_e32 v72, v70, v72
	ds_read_b64_tr_b16 v[204:205], v171 offset:55360
	ds_read_b64_tr_b16 v[206:207], v171 offset:57664
	v_fma_f32 v66, v66, s1, v178
	v_exp_f32_e32 v66, v66
	v_add_f32_e32 v72, v71, v72
	ds_read_b64_tr_b16 v[208:209], v171 offset:55392
	ds_read_b64_tr_b16 v[210:211], v171 offset:57696
	s_waitcnt lgkmcnt(6)
; __device__ __forceinline__ unsigned cvt_pk_bf16(float lo, float hi) { f32x2_t v = {lo, hi}; bf2_t r = __builtin_convertvector(v, bf2_t); return __builtin_bit_cast(unsigned, r); }
; __device__ __forceinline__ s16x4_t lds_tr_b64(const bf16_t* p) { return __builtin_amdgcn_ds_read_tr16_b64_v4i16((LAS s16x4_t*)p); }
; __device__ __forceinline__ void attn_item(const Ctx& C, int it, int itn, u32x4 (&kv)[4], u32x4 (&vv)[4], u32x4 (&qv)[2]) {
;     ...
;     float lsum = 0.f;
; #pragma unroll
;     for (int kt = 0; kt < 9; ++kt)
; #pragma unroll
;         for (int rg = 0; rg < 4; ++rg) { const float s = sc[kt][rg]; const float p = (s > -1e29f) ? __expf(s - mx) : 0.f; sc[kt][rg] = p; lsum += p; }
;     lsum += __shfl_xor(lsum, 16); lsum += __shfl_xor(lsum, 32);
;     f32x4 oo[4];
; #pragma unroll
;     for (int dt = 0; dt < 4; ++dt) oo[dt] = (f32x4){0.f, 0.f, 0.f, 0.f};
; #pragma unroll
;     for (int pp = 0; pp < 5; ++pp) { const int ktA = 2 * pp, ktB = 2 * pp + 1, ktBc = ktB < 9 ? ktB : 8;
;         union { bf16x8 v; unsigned u[4]; } pf;
;         pf.u[0] = cvt_pk_bf16(sc[ktA][0], sc[ktA][1]); pf.u[1] = cvt_pk_bf16(sc[ktA][2], sc[ktA][3]);
;         if (ktB < 9) { pf.u[2] = cvt_pk_bf16(sc[ktBc][0], sc[ktBc][1]); pf.u[3] = cvt_pk_bf16(sc[ktBc][2], sc[ktBc][3]); } else { pf.u[2] = 0u; pf.u[3] = 0u; }
; #pragma unroll
;         for (int dt = 0; dt < 4; ++dt) { const bf16_t* vr = Vs + (16 * w + 4 * quad + (fr >> 2)) * 72 + 16 * dt + 4 * (fr & 3);
;             union { bf16x8 v; s16x4_t h[2]; } vf; vf.h[0] = lds_tr_b64(vr + 16 * ktA * 72); vf.h[1] = lds_tr_b64(vr + 16 * ktBc * 72);
;             oo[dt] = __builtin_amdgcn_mfma_f32_16x16x32_bf16(vf.v, pf.v, oo[dt], 0, 0, 0); } }
	v_mfma_f32_16x16x32_bf16 v[74:77], v[74:77], v[196:199], 0
	v_fma_f32 v69, v69, s1, v178
	v_exp_f32_e32 v69, v69
	v_add_f32_e32 v72, v66, v72
	s_waitcnt lgkmcnt(4)
	v_mfma_f32_16x16x32_bf16 v[200:203], v[200:203], v[196:199], 0
	v_mov_b32_e32 v91, v65
	v_fma_f32 v67, v67, s1, v178
	v_exp_f32_e32 v67, v67
	v_add_f32_e32 v72, v69, v72
	s_waitcnt lgkmcnt(2)
	v_mfma_f32_16x16x32_bf16 v[204:207], v[204:207], v[196:199], 0
	v_fma_f32 v68, v68, s1, v178
	v_exp_f32_e32 v68, v68
	v_add_f32_e32 v72, v67, v72
	s_waitcnt lgkmcnt(0)
	v_mfma_f32_16x16x32_bf16 v[196:199], v[208:211], v[196:199], 0
	v_cvt_pk_bf16_f32 v209, v71, v66
	v_fma_f32 v60, v60, s1, v178
	v_exp_f32_e32 v60, v60
	v_add_f32_e32 v73, v68, v72
	v_cvt_pk_bf16_f32 v210, v69, v67
	v_cvt_pk_bf16_f32 v208, v64, v70
	v_mov_b32_e32 v72, v60
	v_fma_f32 v60, v62, s1, v178
	v_exp_f32_e32 v60, v60
	v_add_f32_e32 v73, v72, v73
	v_cvt_pk_bf16_f32 v211, v68, v72
	v_fma_f32 v61, v61, s1, v178
	v_exp_f32_e32 v61, v61
	v_add_f32_e32 v62, v60, v73
	ds_read_b64_tr_b16 v[66:67], v171 offset:59904
	ds_read_b64_tr_b16 v[68:69], v171 offset:62208
	s_waitcnt lgkmcnt(0)
	v_mfma_f32_16x16x32_bf16 v[66:69], v[66:69], v[208:211], v[74:77]
	v_add_f32_e32 v73, v61, v62
	v_fma_f32 v62, v63, s1, v178
	v_exp_f32_e32 v62, v62
	ds_read_b64_tr_b16 v[74:75], v171 offset:59936
	ds_read_b64_tr_b16 v[76:77], v171 offset:62240
	s_waitcnt lgkmcnt(0)
	v_mfma_f32_16x16x32_bf16 v[74:77], v[74:77], v[208:211], v[200:203]
	v_fma_f32 v57, v57, s1, v178
	v_exp_f32_e32 v57, v57
	v_add_f32_e32 v63, v62, v73
	ds_read_b64_tr_b16 v[200:201], v171 offset:59968
	ds_read_b64_tr_b16 v[202:203], v171 offset:62272
	s_waitcnt lgkmcnt(0)
	v_mfma_f32_16x16x32_bf16 v[200:203], v[200:203], v[208:211], v[204:207]
	v_fma_f32 v59, v59, s1, v178
	v_exp_f32_e32 v59, v59
	v_add_f32_e32 v63, v57, v63
	ds_read_b64_tr_b16 v[204:205], v171 offset:60000
	ds_read_b64_tr_b16 v[206:207], v171 offset:62304
	v_cvt_pk_bf16_f32 v60, v60, v61
	v_fma_f32 v56, v56, s1, v178
	v_exp_f32_e32 v56, v56
	v_add_f32_e32 v63, v59, v63
	v_cvt_pk_bf16_f32 v61, v62, v57
	s_waitcnt lgkmcnt(0)
	v_mfma_f32_16x16x32_bf16 v[196:199], v[204:207], v[208:211], v[196:199]
	v_fma_f32 v58, v58, s1, v178
	v_exp_f32_e32 v58, v58
	v_add_f32_e32 v63, v56, v63
	v_cvt_pk_bf16_f32 v62, v59, v56
	v_mov_b32_e32 v64, v65
	v_fma_f32 v53, v53, s1, v178
	v_exp_f32_e32 v53, v53
	v_add_f32_e32 v73, v58, v63
	v_mov_b32_e32 v63, v53
	v_fma_f32 v53, v55, s1, v178
	v_exp_f32_e32 v53, v53
	v_add_f32_e32 v73, v63, v73
	v_cvt_pk_bf16_f32 v63, v58, v63
	v_fma_f32 v52, v52, s1, v178
	v_exp_f32_e32 v52, v52
	ds_read_b64_tr_b16 v[56:57], v171 offset:64512
	ds_read_b64_tr_b16 v[58:59], v172 offset:11520
	ds_read_b64_tr_b16 v[70:71], v172 offset:11552
	v_add_f32_e32 v55, v53, v73
	s_waitcnt lgkmcnt(1)
	v_mfma_f32_16x16x32_bf16 v[56:59], v[56:59], v[60:63], v[66:69]
	v_fma_f32 v54, v54, s1, v178
	v_exp_f32_e32 v54, v54
	v_add_f32_e32 v55, v52, v55
	ds_read_b64_tr_b16 v[68:69], v171 offset:64544
	s_waitcnt lgkmcnt(0)
	v_mfma_f32_16x16x32_bf16 v[66:69], v[68:71], v[60:63], v[74:77]
	v_fma_f32 v49, v49, s1, v178
	v_exp_f32_e32 v49, v49
	v_add_f32_e32 v55, v54, v55
	ds_read_b64_tr_b16 v[74:75], v171 offset:64576
	ds_read_b64_tr_b16 v[76:77], v172 offset:11584
	s_waitcnt lgkmcnt(0)
	v_mfma_f32_16x16x32_bf16 v[74:77], v[74:77], v[60:63], v[200:203]
	v_fma_f32 v50, v50, s1, v178
	v_exp_f32_e32 v50, v50
	v_add_f32_e32 v55, v49, v55
	ds_read_b64_tr_b16 v[200:201], v171 offset:64608
	ds_read_b64_tr_b16 v[202:203], v172 offset:11616
	v_cvt_pk_bf16_f32 v52, v53, v52
	v_fma_f32 v48, v48, s1, v178
	v_exp_f32_e32 v48, v48
	v_add_f32_e32 v73, v50, v55
	v_cvt_pk_bf16_f32 v53, v54, v49
	s_waitcnt lgkmcnt(0)
	v_mfma_f32_16x16x32_bf16 v[60:63], v[200:203], v[60:63], v[196:199]
	v_mov_b32_e32 v55, v48
	v_fma_f32 v45, v45, s1, v178
	v_exp_f32_e32 v45, v45
	v_add_f32_e32 v48, v55, v73
	v_cvt_pk_bf16_f32 v54, v50, v55
	v_mov_b32_e32 v73, v45
	v_fma_f32 v44, v44, s1, v178
	v_exp_f32_e32 v44, v44
	v_add_f32_e32 v45, v73, v48
	v_mov_b32_e32 v194, v44
	v_add_f32_e32 v44, v194, v45
	v_fma_f32 v45, v47, s1, v178
	v_cvt_pk_bf16_f32 v55, v73, v194
	ds_read_b64_tr_b16 v[70:71], v172 offset:13824
	ds_read_b64_tr_b16 v[72:73], v172 offset:16128
	v_exp_f32_e32 v45, v45
	s_waitcnt lgkmcnt(0)
	v_mfma_f32_16x16x32_bf16 v[56:59], v[70:73], v[52:55], v[56:59]
	ds_read_b64_tr_b16 v[70:71], v172 offset:13856
	ds_read_b64_tr_b16 v[72:73], v172 offset:16160
	v_fma_f32 v46, v46, s1, v178
	v_fma_f32 v47, v51, s1, v178
	v_exp_f32_e32 v46, v46
	v_exp_f32_e32 v47, v47
	s_waitcnt lgkmcnt(0)
	v_mfma_f32_16x16x32_bf16 v[66:69], v[70:73], v[52:55], v[66:69]
	ds_read_b64_tr_b16 v[70:71], v172 offset:13888
	ds_read_b64_tr_b16 v[72:73], v172 offset:16192
	s_waitcnt lgkmcnt(0)
	v_mfma_f32_16x16x32_bf16 v[70:73], v[70:73], v[52:55], v[74:77]
	v_fma_f32 v41, v41, s1, v178
	v_exp_f32_e32 v41, v41
	ds_read_b64_tr_b16 v[74:75], v172 offset:13920
	ds_read_b64_tr_b16 v[76:77], v172 offset:16224
	v_add_f32_e32 v44, v45, v44
	v_add_f32_e32 v44, v46, v44
	v_mov_b32_e32 v48, v41
	v_add_f32_e32 v44, v47, v44
	s_waitcnt lgkmcnt(0)
	v_mfma_f32_16x16x32_bf16 v[50:53], v[74:77], v[52:55], v[60:63]
	v_add_f32_e32 v41, v48, v44
	ds_bpermute_b32 v44, v169, v41
	ds_read_b64_tr_b16 v[54:55], v172 offset:18464
	v_cvt_pk_bf16_f32 v62, v45, v46
	v_cvt_pk_bf16_f32 v63, v47, v48
	ds_read_b64_tr_b16 v[46:47], v172 offset:18432
	s_waitcnt lgkmcnt(2)
	v_add_f32_e32 v41, v41, v44
	ds_bpermute_b32 v44, v170, v41
	s_lshl_b32 s1, s51, 12
	s_or_b32 s0, s0, s1
	s_waitcnt lgkmcnt(1)
	v_mov_b32_e32 v48, v46
	v_mov_b32_e32 v49, v47
	s_waitcnt lgkmcnt(0)
	v_add_f32_e32 v41, v41, v44
	v_div_scale_f32 v40, s[48:49], v41, v41, 1.0
	v_mfma_f32_16x16x32_bf16 v[46:49], v[46:49], v[62:65], v[56:59]
	v_rcp_f32_e32 v43, v40
	s_nop 1
	v_mov_b32_e32 v56, v54
	v_mov_b32_e32 v57, v55
	ds_read_b64_tr_b16 v[58:59], v172 offset:18496
	v_fma_f32 v44, -v40, v43, 1.0
	v_mfma_f32_16x16x32_bf16 v[54:57], v[54:57], v[62:65], v[66:69]
	v_fmac_f32_e32 v43, v44, v43
	s_nop 1
	ds_read_b64_tr_b16 v[66:67], v172 offset:18528
	s_waitcnt lgkmcnt(1)
	v_mov_b32_e32 v60, v58
	v_mov_b32_e32 v61, v59
	v_div_scale_f32 v44, vcc, 1.0, v41, 1.0
	s_waitcnt lgkmcnt(0)
	v_mov_b32_e32 v68, v66
	v_mov_b32_e32 v69, v67
	v_mul_f32_e32 v45, v44, v43
	v_mfma_f32_16x16x32_bf16 v[58:61], v[58:61], v[62:65], v[70:73]
	s_barrier
; __device__ __forceinline__ unsigned cvt_pk_bf16(float lo, float hi) { f32x2_t v = {lo, hi}; bf2_t r = __builtin_convertvector(v, bf2_t); return __builtin_bit_cast(unsigned, r); }
;     __device__ __forceinline__ float* fp(size_t off) const { return (float*)(ws + off); }
; __device__ __forceinline__ void attn_item(const Ctx& C, int it, int itn, u32x4 (&kv)[4], u32x4 (&vv)[4], u32x4 (&qv)[2]) {
;     ...
;     const float inv = 1.0f / lsum;
;     const size_t tok = (size_t)(b * SEQ + r + dil * (128 * jb + a));
;     __syncthreads();
; #pragma unroll
;     for (int dt = 0; dt < 4; ++dt) { u32x2 o; o.x = cvt_pk_bf16(oo[dt][0] * inv, oo[dt][1] * inv); o.y = cvt_pk_bf16(oo[dt][2] * inv, oo[dt][3] * inv);
;         *(u32x2*)(pd + tok * 2304 + hq * 64 + 16 * dt + 4 * quad) = o; }
;     if (quad == 0) C.fp(OFF_LSE)[((size_t)g * M_TOK + tok) * 4 + (hq & 3)] = mx + __logf(lsum);
	v_mfma_f32_16x16x32_bf16 v[50:53], v[66:69], v[62:65], v[50:53]
	v_fma_f32 v62, -v40, v45, v44
	v_fmac_f32_e32 v45, v62, v43
	v_fma_f32 v40, -v40, v45, v44
	v_div_fmas_f32 v40, v40, v43, v45
	v_div_fixup_f32 v44, v40, v41, 1.0
	v_add_u32_e32 v40, s46, v83
	v_lshlrev_b32_e32 v40, s52, v40
	v_add_u32_e32 v40, s0, v40
	v_mov_b64_e32 v[62:63], s[42:43]
	v_mad_i64_i32 v[62:63], s[0:1], v40, s66, v[62:63]
	s_lshl_b32 s0, s41, 6
	s_ashr_i32 s1, s0, 31
	v_lshl_add_u64 v[62:63], s[0:1], 1, v[62:63]
	v_pk_mul_f32 v[46:47], v[44:45], v[46:47] op_sel_hi:[0,1]
	v_pk_mul_f32 v[48:49], v[44:45], v[48:49] op_sel_hi:[0,1]
	v_lshl_add_u64 v[62:63], v[62:63], 0, v[90:91]
	v_cvt_pk_bf16_f32 v46, v46, v47
	v_cvt_pk_bf16_f32 v47, v48, v49
	global_store_dwordx2 v[62:63], v[46:47], off
	v_pk_mul_f32 v[46:47], v[44:45], v[54:55] op_sel_hi:[0,1]
	v_pk_mul_f32 v[48:49], v[44:45], v[56:57] op_sel_hi:[0,1]
	v_cvt_pk_bf16_f32 v46, v46, v47
	v_cvt_pk_bf16_f32 v47, v48, v49
	global_store_dwordx2 v[62:63], v[46:47], off offset:32
	v_pk_mul_f32 v[46:47], v[44:45], v[58:59] op_sel_hi:[0,1]
	v_pk_mul_f32 v[48:49], v[44:45], v[60:61] op_sel_hi:[0,1]
	v_cvt_pk_bf16_f32 v46, v46, v47
	v_cvt_pk_bf16_f32 v47, v48, v49
	global_store_dwordx2 v[62:63], v[46:47], off offset:64
	v_pk_mul_f32 v[46:47], v[44:45], v[50:51] op_sel_hi:[0,1]
	v_pk_mul_f32 v[44:45], v[44:45], v[52:53] op_sel_hi:[0,1]
	v_cvt_pk_bf16_f32 v46, v46, v47
	v_cvt_pk_bf16_f32 v47, v44, v45
	global_store_dwordx2 v[62:63], v[46:47], off offset:96
	s_and_saveexec_b64 s[0:1], s[20:21]
	s_cbranch_execz .LBB0_344
	v_cmp_gt_f32_e32 vcc, s54, v41
	s_ashr_i32 s41, s40, 31
	s_lshl_b64 s[40:41], s[40:41], 19
	v_cndmask_b32_e64 v43, 0, 32, vcc
	v_ldexp_f32 v41, v41, v43
	v_log_f32_e32 v43, v41
	v_readlane_b32 s46, v255, 43
	v_cndmask_b32_e32 v44, 0, v225, vcc
	s_add_u32 s40, s46, s40
	v_mul_f32_e32 v45, 0x3f317217, v43
	v_fma_f32 v45, v43, s56, -v45
	v_fmac_f32_e32 v45, 0x3377d1cf, v43
	v_fmac_f32_e32 v45, 0x3f317217, v43
	v_cmp_lt_f32_e64 vcc, |v43|, s57
	v_readlane_b32 s46, v255, 44
	v_ashrrev_i32_e32 v41, 31, v40
	v_cndmask_b32_e32 v43, v43, v45, vcc
	s_addc_u32 s41, s46, s41
	s_lshr_b32 s36, s36, 3
	v_sub_f32_e32 v43, v43, v44
	v_lshl_add_u64 v[40:41], v[40:41], 4, s[40:41]
	s_and_b32 s36, s36, 12
	v_add_f32_e32 v42, v42, v43
	v_lshl_add_u64 v[40:41], v[40:41], 0, s[36:37]
	global_store_dword v[40:41], v42, off
	s_branch .LBB0_344
